# first seam: cooperative-groups grid sync replaced by the kernel's own XCD-hierarchical barrier (same wbl2/inv fences, one L2 writeback per XCD instead of one per workgroup)
# speedup vs baseline: 1.0151x; 1.0083x over previous
.LBB0_49:
	s_or_b64 exec, exec, s[0:1]
	v_lshrrev_b32_e32 v1, 20, v0
	v_lshrrev_b32_e32 v0, 10, v0
	v_or_b32_e32 v0, v0, v1
	s_movk_i32 s0, 0x3ff
	v_and_or_b32 v0, v0, s0, v194
	v_cmp_eq_u32_e32 vcc, 0, v0
	s_waitcnt lgkmcnt(0)
	s_barrier
	s_mov_b64 s[0:1], exec
.LBB0_59:
	v_writelane_b32 v246, s36, 2
	s_nop 1
	v_writelane_b32 v246, s37, 3
	s_or_b64 exec, exec, s[0:1]
	s_cmpk_lt_i32 s2, 0x380
	s_cselect_b64 s[0:1], -1, 0
	v_writelane_b32 v246, s0, 4
	s_ashr_i32 s3, s2, 31
	s_ashr_i32 s31, s92, 31
	v_writelane_b32 v246, s1, 5
	s_lshr_b32 s0, s3, 29
	s_add_i32 s0, s2, s0
	s_ashr_i32 s10, s0, 3
	s_and_b32 s0, s0, -8
	s_sub_i32 s11, s2, s0
	s_cmpk_gt_i32 s2, 0x7f
	s_cselect_b64 s[0:1], -1, 0
	v_writelane_b32 v246, s0, 6
	s_add_i32 s24, s8, 0xfffffc00
	s_movk_i32 s18, 0x161
	v_writelane_b32 v246, s1, 7
	s_add_i32 s0, s28, 0xfffffc00
	v_writelane_b32 v246, s0, 8
	s_add_u32 s0, s58, 0x400000
	s_addc_u32 s1, s59, 0
	v_writelane_b32 v246, s0, 9
	v_mov_b64_e32 v[156:157], 0x200
	s_mov_b32 s37, 0
	v_writelane_b32 v246, s1, 10
	s_mul_i32 s93, s93, s92
	v_readlane_b32 s60, v246, 11
	v_readlane_b32 s66, v246, 17
	v_readlane_b32 s72, v246, 23
	v_readlane_b32 s67, v246, 18
	v_readlane_b32 s73, v246, 24
	s_add_u32 s66, s72, 0x1000
	v_readlane_b32 s74, v246, 25
	s_addc_u32 s67, s73, 0
	v_readlane_b32 s75, v246, 26
	s_add_u32 s0, s74, 0x1600000
	s_addc_u32 s1, s75, 0
	v_readlane_b32 s61, v246, 12
	v_readlane_b32 s62, v246, 13
	v_readlane_b32 s63, v246, 14
	v_readlane_b32 s64, v246, 15
	v_readlane_b32 s65, v246, 16
	v_readlane_b32 s68, v246, 19
	v_readlane_b32 s69, v246, 20
	v_readlane_b32 s70, v246, 21
	v_readlane_b32 s71, v246, 22
	v_writelane_b32 v246, s0, 27
	s_cmp_lg_u64 s[72:73], 0
	s_mul_i32 s93, s93, s26
	v_writelane_b32 v246, s1, 28
	s_cselect_b64 s[0:1], -1, 0
	s_add_u32 s4, s40, 0xb00000
	s_addc_u32 s5, s41, 0
	v_writelane_b32 v246, s4, 29
	s_cmpk_lt_i32 s2, 0x680
	v_mov_b32_e32 v3, 0
	v_writelane_b32 v246, s5, 30
	s_cselect_b64 s[4:5], -1, 0
	s_add_i32 s9, s2, 0x80
	v_writelane_b32 v246, s4, 31
	s_cmpk_gt_i32 s2, 0x9f
	v_mov_b32_e32 v195, 0x358637bd
	v_writelane_b32 v246, s5, 32
	s_cselect_b64 s[4:5], -1, 0
	v_writelane_b32 v246, s4, 33
	s_add_i32 s25, s8, 0xfffffb00
	s_mul_i32 s8, s2, 6
	v_writelane_b32 v246, s5, 34
	s_add_i32 s4, s28, 0xfffffb00
	v_writelane_b32 v246, s4, 35
	s_add_u32 s56, s52, 0x1000
	v_writelane_b32 v246, s48, 36
	v_mov_b32_e32 v196, 1
	v_mov_b64_e32 v[158:159], 0x380
	v_writelane_b32 v246, s49, 37
	v_writelane_b32 v246, s50, 38
	v_writelane_b32 v246, s51, 39
	v_writelane_b32 v246, s52, 40
	v_writelane_b32 v246, s53, 41
	v_writelane_b32 v246, s54, 42
	v_writelane_b32 v246, s55, 43
	v_writelane_b32 v246, s56, 44
	v_writelane_b32 v246, s57, 45
	v_writelane_b32 v246, s58, 46
	v_writelane_b32 v246, s59, 47
	v_writelane_b32 v246, s60, 48
	v_writelane_b32 v246, s61, 49
	v_writelane_b32 v246, s62, 50
	v_writelane_b32 v246, s63, 51
	s_addc_u32 s57, s53, 0
	s_mov_b64 s[48:49], s[0:1]
	s_add_u32 s0, s46, 0x3310200
	s_addc_u32 s1, s47, 0
	s_add_u32 s38, s46, 0x3310400
	s_addc_u32 s39, s47, 0
	s_add_u32 s50, s46, 0x3310500
	v_writelane_b32 v246, s0, 52
	s_addc_u32 s51, s47, 0
	v_mov_b64_e32 v[160:161], 0x37f
	v_writelane_b32 v246, s1, 53
	s_add_u32 s0, s46, 0x3310600
	s_addc_u32 s1, s47, 0
	v_writelane_b32 v246, s0, 54
	v_mbcnt_hi_u32_b32 v197, -1, v62
	v_mov_b64_e32 v[162:163], 0x680
	v_writelane_b32 v246, s1, 55
	s_add_u32 s0, s46, 0x3310700
	s_addc_u32 s1, s47, 0
	v_writelane_b32 v246, s0, 56
	v_mov_b64_e32 v[164:165], 0x67f
	v_mov_b32_e32 v198, 0x600000
	v_writelane_b32 v246, s1, 57
	s_add_u32 s0, s46, 0x3310800
	s_addc_u32 s1, s47, 0
	v_writelane_b32 v246, s0, 58
	v_mov_b64_e32 v[166:167], 0x1ff
	v_mov_b64_e32 v[168:169], 0xb00
	v_writelane_b32 v246, s1, 59
	s_add_u32 s0, s46, 0x3310900
	s_addc_u32 s1, s47, 0
	v_writelane_b32 v246, s0, 60
	v_mov_b64_e32 v[170:171], 0xaff
	s_movk_i32 s95, 0x600
	v_writelane_b32 v246, s1, 61
	s_add_u32 s0, s46, 0x3310a00
	s_addc_u32 s1, s47, 0
	v_writelane_b32 v246, s0, 62
	s_movk_i32 s36, 0x2000
	s_movk_i32 s33, 0x5800
	v_writelane_b32 v246, s1, 63
	s_add_u32 s0, s46, 0x3310b00
	s_addc_u32 s1, s47, 0
	v_writelane_b32 v245, s0, 0
	s_movk_i32 s59, 0x1c00
	s_mov_b32 s85, 0x428c0000
	v_writelane_b32 v245, s1, 1
	s_add_u32 s0, s46, 0x3310c00
	s_addc_u32 s1, s47, 0
	v_writelane_b32 v245, s0, 2
	s_movk_i32 s53, 0x1600
	s_mov_b64 s[96:97], -1
	v_writelane_b32 v245, s1, 3
	s_add_u32 s0, s46, 0x3310d00
	s_addc_u32 s1, s47, 0
	v_writelane_b32 v245, s0, 4
	s_mov_b32 s52, 0x3e6d3388
	s_mov_b32 s62, 0x3f07dc22
	v_writelane_b32 v245, s1, 5
	s_add_u32 s0, s46, 0x3310e00
	s_addc_u32 s1, s47, 0
	v_writelane_b32 v245, s0, 6
	s_mov_b32 s30, 0x3f35f0e3
	s_mov_b32 s94, 0xbe11a98e
	v_writelane_b32 v245, s1, 7
	s_add_u32 s0, s46, 0x3310f00
	s_addc_u32 s1, s47, 0
	v_writelane_b32 v245, s0, 8
	s_mov_b32 s84, 0x3e027906
	s_mov_b32 s86, 0xbf38aa3b
	v_writelane_b32 v245, s1, 9
	s_add_u32 s0, s46, 0x3311000
	s_addc_u32 s1, s47, 0
	v_writelane_b32 v245, s0, 10
	s_mov_b32 s88, 0x3e38aa3b
	s_mov_b32 s90, 0xbfb8aa3b
	v_writelane_b32 v245, s1, 11
	s_add_u32 s0, s46, 0x3311100
	s_addc_u32 s1, s47, 0
	v_writelane_b32 v245, s0, 12
	s_mov_b32 s58, 0x3f317218
	v_writelane_b32 v242, s50, 0
	v_writelane_b32 v245, s1, 13
	s_add_u32 s0, s46, 0x3311200
	s_addc_u32 s1, s47, 0
	v_writelane_b32 v245, s0, 14
	s_barrier
	s_nop 0
	v_writelane_b32 v245, s1, 15
	s_add_u32 s0, s46, 0x3311300
	s_addc_u32 s1, s47, 0
	v_writelane_b32 v245, s0, 16
	s_cmp_eq_u32 s27, 15
	v_writelane_b32 v242, s51, 1
	v_writelane_b32 v245, s1, 17
	s_cselect_b64 s[0:1], -1, 0
	v_writelane_b32 v245, s0, 18
	s_cmp_eq_u32 s27, 14
	s_nop 0
	v_writelane_b32 v245, s1, 19
	s_cselect_b64 s[0:1], -1, 0
	v_writelane_b32 v245, s0, 20
	s_cmp_eq_u32 s27, 13
	s_nop 0
	v_writelane_b32 v245, s1, 21
	s_cselect_b64 s[0:1], -1, 0
	v_writelane_b32 v245, s0, 22
	s_cmp_eq_u32 s27, 12
	s_nop 0
	v_writelane_b32 v245, s1, 23
	s_cselect_b64 s[0:1], -1, 0
	v_writelane_b32 v245, s0, 24
	s_cmp_eq_u32 s27, 11
	s_nop 0
	v_writelane_b32 v245, s1, 25
	s_cselect_b64 s[0:1], -1, 0
	v_writelane_b32 v245, s0, 26
	s_cmp_eq_u32 s27, 10
	s_nop 0
	v_writelane_b32 v245, s1, 27
	s_cselect_b64 s[0:1], -1, 0
	v_writelane_b32 v245, s0, 28
	s_cmp_eq_u32 s27, 9
	s_nop 0
	v_writelane_b32 v245, s1, 29
	s_cselect_b64 s[0:1], -1, 0
	v_writelane_b32 v245, s0, 30
	s_cmp_eq_u32 s27, 8
	s_nop 0
	v_writelane_b32 v245, s1, 31
	s_cselect_b64 s[0:1], -1, 0
	v_writelane_b32 v245, s0, 32
	s_cmp_eq_u32 s27, 7
	s_nop 0
	v_writelane_b32 v245, s1, 33
	s_cselect_b64 s[0:1], -1, 0
	v_writelane_b32 v245, s0, 34
	s_cmp_eq_u32 s27, 6
	s_nop 0
	v_writelane_b32 v245, s1, 35
	s_cselect_b64 s[0:1], -1, 0
	v_writelane_b32 v245, s0, 36
	s_cmp_eq_u32 s27, 5
	s_nop 0
	v_writelane_b32 v245, s1, 37
	s_cselect_b64 s[0:1], -1, 0
	v_writelane_b32 v245, s0, 38
	s_cmp_eq_u32 s27, 4
	s_nop 0
	v_writelane_b32 v245, s1, 39
	s_cselect_b64 s[0:1], -1, 0
	v_writelane_b32 v245, s0, 40
	s_cmp_eq_u32 s27, 3
	s_nop 0
	v_writelane_b32 v245, s1, 41
	s_cselect_b64 s[0:1], -1, 0
	v_writelane_b32 v245, s0, 42
	s_cmp_eq_u32 s27, 2
	s_nop 0
	v_writelane_b32 v245, s1, 43
	s_cselect_b64 s[0:1], -1, 0
	v_writelane_b32 v245, s0, 44
	s_cmp_eq_u32 s27, 1
	s_nop 0
	v_writelane_b32 v245, s1, 45
	s_cselect_b64 s[0:1], -1, 0
	v_writelane_b32 v245, s0, 46
	s_cmp_eq_u32 s27, 0
	s_nop 0
	v_writelane_b32 v245, s1, 47
	s_cselect_b64 s[0:1], -1, 0
	v_writelane_b32 v245, s0, 48
	s_nop 1
	v_writelane_b32 v245, s1, 49
	s_lshl_b32 s0, s27, 8
	s_add_u32 s0, s6, s0
	s_addc_u32 s1, s7, 0
	s_add_u32 s4, s0, 0x1400
	s_addc_u32 s5, s1, 0
	v_writelane_b32 v245, s4, 50
	s_add_u32 s0, s0, 0x2400
	s_addc_u32 s1, s1, 0
	v_writelane_b32 v245, s5, 51
	v_writelane_b32 v245, s0, 52
	s_nop 1
	v_writelane_b32 v245, s1, 53
	s_add_u32 s0, s46, 0x3313400
	s_addc_u32 s1, s47, 0
	v_writelane_b32 v245, s0, 54
	s_nop 1
	v_writelane_b32 v245, s1, 55
	s_add_u32 s0, s46, 0x3313500
	s_addc_u32 s1, s47, 0
	v_writelane_b32 v245, s0, 56
	s_cmpk_lt_i32 s2, 0x600
	s_cselect_b64 s[4:5], -1, 0
	v_writelane_b32 v245, s1, 57
	s_mul_hi_i32 s0, s2, 0x2aaaaaab
	s_lshr_b32 s1, s0, 31
	s_add_i32 s0, s0, s1
	s_lshl_b32 s1, s0, 7
	s_mul_i32 s0, s0, 6
	v_writelane_b32 v245, s4, 58
	s_sub_i32 s0, s2, s0
	s_lshl_b32 s0, s0, 7
	v_writelane_b32 v245, s5, 59
	v_writelane_b32 v245, s1, 60
	s_ashr_i32 s1, s0, 31
	v_writelane_b32 v245, s0, 61
	s_lshl_b32 s28, s2, 6
	s_and_b32 s4, s28, 0xc0
	v_writelane_b32 v245, s1, 62
	s_lshl_b32 s0, s2, 2
	s_and_b32 s0, s0, 0xffffff00
	s_cmpk_lt_i32 s2, 0xc0
	v_writelane_b32 v245, s0, 63
	s_cselect_b64 s[0:1], -1, 0
	v_writelane_b32 v244, s0, 0
	s_nop 1
	v_writelane_b32 v244, s1, 1
	s_ashr_i32 s0, s2, 2
	s_mul_hi_i32 s1, s0, 0x2aaaaaab
	s_lshr_b32 s5, s1, 31
	s_add_i32 s5, s1, s5
	s_mul_i32 s1, s5, 6
	s_sub_i32 s0, s0, s1
	s_ashr_i32 s1, s0, 31
	s_lshl_b64 s[12:13], s[0:1], 7
	s_lshl_b32 s29, s5, 12
	s_lshl_b32 s5, s2, 10
	v_writelane_b32 v244, s12, 2
	s_and_b32 s6, s5, 0xc00
	s_lshl_b32 s5, s2, 5
	v_writelane_b32 v244, s13, 3
	v_writelane_b32 v244, s5, 4
	s_lshl_b32 s0, s0, 7
	v_writelane_b32 v244, s6, 5
	s_lshl_b32 s5, s2, 7
	s_ashr_i32 s1, s0, 31
	s_or_b32 s6, s6, 0x3e0
	v_writelane_b32 v244, s5, 6
	s_lshl_b64 s[12:13], s[2:3], 16
	v_writelane_b32 v244, s12, 7
	s_cmpk_gt_i32 s2, 0xbf
	s_nop 0
	v_writelane_b32 v244, s13, 8
	s_cselect_b64 s[12:13], -1, 0
	v_writelane_b32 v244, s12, 9
	s_add_i32 s7, s2, 0xffffff40
	s_add_i32 s5, s92, 0xffffff40
	v_writelane_b32 v244, s13, 10
	s_cmpk_lt_u32 s7, 0x200
	v_writelane_b32 v244, s5, 11
	s_cselect_b64 s[12:13], -1, 0
	v_writelane_b32 v244, s12, 12
	s_lshl_b32 s5, s7, 2
	s_and_b32 s5, s5, 0x700
	v_writelane_b32 v244, s13, 13
	v_writelane_b32 v244, s5, 14
	v_writelane_b32 v244, s7, 15
	s_lshl_b32 s5, s7, 6
	s_add_i32 s7, s8, 5
	s_ashr_i32 s15, s8, 3
	s_and_b32 s5, s5, 0xc0
	s_ashr_i32 s7, s7, 3
	s_and_b32 s8, s15, 3
	s_cmp_lg_u32 s8, 0
	s_cselect_b64 s[12:13], -1, 0
	v_writelane_b32 v244, s12, 16
	s_nop 1
	v_writelane_b32 v244, s13, 17
	s_and_b32 s12, s15, -4
	s_ashr_i32 s13, s12, 31
	s_lshl_b32 s14, s12, 7
	s_lshl_b64 s[12:13], s[12:13], 16
	v_writelane_b32 v244, s12, 18
	s_nop 1
	v_writelane_b32 v244, s13, 19
	s_or_b32 s12, s14, 0x80
	v_writelane_b32 v244, s12, 20
	s_or_b32 s12, s14, 0x100
	s_cmp_lg_u32 s8, 1
	v_writelane_b32 v244, s12, 21
	s_cselect_b64 s[12:13], -1, 0
	v_writelane_b32 v244, s12, 22
	s_cmp_eq_u32 s8, 3
	s_nop 0
	v_writelane_b32 v244, s13, 23
	s_cselect_b64 s[12:13], -1, 0
	v_writelane_b32 v244, s12, 24
	s_cmp_lg_u32 s7, s15
	s_nop 0
	v_writelane_b32 v244, s13, 25
	s_cselect_b64 s[12:13], -1, 0
	s_and_b32 s8, s7, 3
	s_cmp_lg_u32 s8, 0
	v_writelane_b32 v244, s15, 26
	s_cselect_b64 s[14:15], -1, 0
	s_and_b32 s16, s7, -4
	s_ashr_i32 s17, s16, 31
	s_lshl_b32 s7, s16, 7
	s_lshl_b64 s[16:17], s[16:17], 16
	v_writelane_b32 v244, s16, 27
	s_nop 1
	v_writelane_b32 v244, s17, 28
	s_or_b32 s16, s7, 0x80
	s_bitset1_b32 s7, 8
	v_writelane_b32 v244, s16, 29
	s_cmp_lg_u32 s8, 1
	v_writelane_b32 v244, s7, 30
	s_cselect_b64 s[16:17], -1, 0
	v_writelane_b32 v244, s16, 31
	s_cmp_eq_u32 s8, 3
	s_nop 0
	v_writelane_b32 v244, s17, 32
	s_cselect_b64 s[16:17], -1, 0
	v_writelane_b32 v244, s16, 33
	s_cmpk_lt_i32 s2, 0x200
	s_nop 0
	v_writelane_b32 v244, s17, 34
	s_cselect_b64 s[16:17], -1, 0
	s_lshl_b32 s8, s11, 6
	v_writelane_b32 v244, s16, 35
	s_cmpk_lt_i32 s2, 0xb00
	s_nop 0
	v_writelane_b32 v244, s17, 36
	s_cselect_b64 s[16:17], -1, 0
	v_writelane_b32 v244, s16, 37
	s_add_i32 s7, s92, 0x1ff
	s_cmp_lt_i32 s11, 0
	v_writelane_b32 v244, s17, 38
	s_mul_i32 s16, s11, 0x41
	s_cselect_b32 s8, s16, s8
	s_movk_i32 s16, 0x71
	s_movk_i32 s17, 0xd1
	s_cselect_b32 s16, s16, 0x70
	s_cselect_b32 s17, s17, 0xd0
	s_cselect_b32 s18, s18, 0x160
	s_and_b64 s[12:13], s[12:13], s[14:15]
	v_writelane_b32 v244, s12, 39
	s_add_i32 s8, s8, s10
	s_nop 0
	v_writelane_b32 v244, s13, 40
	s_mul_i32 s12, s11, s16
	s_add_i32 s12, s12, s10
	s_mul_hi_i32 s13, s12, 0x92492493
	s_add_i32 s13, s13, s12
	s_lshr_b32 s14, s13, 31
	s_ashr_i32 s13, s13, 5
	s_add_i32 s13, s13, s14
	s_mul_i32 s14, s13, 56
	s_sub_i32 s12, s12, s14
	s_bfe_i32 s14, s12, 0x80000
	s_bfe_u32 s14, s14, 0x3000c
	s_add_i32 s14, s12, s14
	s_and_b32 s15, s14, 0xf8
	s_sub_i32 s12, s12, s15
	s_mul_i32 s15, s11, s17
	s_add_i32 s15, s15, s10
	s_mul_hi_i32 s16, s15, 0x4ec4ec4f
	s_lshr_b32 s17, s16, 31
	s_ashr_i32 s16, s16, 5
	s_add_i32 s16, s16, s17
	s_mul_i32 s17, s16, 0x68
	s_sub_i32 s15, s15, s17
	s_bfe_i32 s17, s15, 0x80000
	s_bfe_u32 s17, s17, 0x3000c
	s_add_i32 s17, s15, s17
	s_and_b32 s19, s17, 0xf8
	s_sub_i32 s15, s15, s19
	s_ashr_i32 s19, s8, 31
	s_mul_i32 s11, s11, s18
	s_lshr_b32 s19, s19, 27
	s_add_i32 s11, s11, s10
	s_add_i32 s19, s8, s19
	s_mul_hi_i32 s10, s11, 0x2e8ba2e9
	s_and_b32 s20, s19, 0xffe0
	s_lshr_b32 s18, s10, 31
	s_ashr_i32 s10, s10, 5
	s_sub_i32 s8, s8, s20
	s_add_i32 s10, s10, s18
	s_bfe_i32 s20, s8, 0x80000
	s_mul_i32 s18, s10, 0xb0
	s_bfe_u32 s20, s20, 0x3000c
	s_sub_i32 s11, s11, s18
	s_add_i32 s20, s8, s20
	s_bfe_u32 s18, s11, 0x3001c
	s_lshl_b32 s13, s13, 3
	s_sext_i32_i8 s12, s12
	s_and_b32 s21, s20, 0xf8
	s_add_i32 s18, s11, s18
	s_add_i32 s34, s13, s12
	s_lshl_b32 s12, s16, 3
	s_sext_i32_i8 s15, s15
	s_sub_i32 s8, s8, s21
	s_and_b32 s21, s18, 0xfff8
	s_add_i32 s16, s12, s15
	s_ashr_i32 s12, s19, 5
	s_sub_i32 s11, s11, s21
	s_lshl_b32 s12, s12, 3
	s_sext_i32_i8 s8, s8
	s_add_i32 s12, s12, s8
	s_lshl_b32 s8, s10, 3
	s_sext_i32_i16 s10, s18
	s_sext_i32_i16 s11, s11
	s_add_i32 s18, s8, s11
	s_ashr_i32 s8, s10, 3
	v_writelane_b32 v244, s8, 41
	s_lshr_b32 s8, s10, 3
	s_bfe_i64 s[10:11], s[8:9], 0x100000
	s_bfe_i32 s14, s14, 0x80000
	s_lshl_b64 s[10:11], s[10:11], 19
	s_sext_i32_i16 s14, s14
	v_writelane_b32 v244, s10, 42
	s_ashr_i32 s8, s14, 3
	s_bfe_i32 s13, s17, 0x80000
	v_writelane_b32 v244, s11, 43
	v_writelane_b32 v244, s8, 44
	s_lshr_b32 s8, s14, 3
	s_bfe_i64 s[10:11], s[8:9], 0x100000
	s_lshl_b64 s[10:11], s[10:11], 19
	s_sext_i32_i16 s13, s13
	v_writelane_b32 v244, s10, 45
	s_ashr_i32 s8, s13, 3
	s_abs_i32 s21, s92
	v_writelane_b32 v244, s11, 46
	v_writelane_b32 v244, s8, 47
	s_lshr_b32 s8, s13, 3
	s_bfe_i64 s[10:11], s[8:9], 0x100000
	s_bfe_i32 s15, s20, 0x80000
	s_lshl_b64 s[10:11], s[10:11], 19
	v_cvt_f32_u32_e32 v0, s21
	s_sext_i32_i16 s15, s15
	v_writelane_b32 v244, s10, 48
	s_ashr_i32 s8, s15, 3
	v_rcp_iflag_f32_e32 v0, v0
	v_writelane_b32 v244, s11, 49
	v_writelane_b32 v244, s8, 50
	s_lshr_b32 s8, s15, 3
	s_bfe_i64 s[10:11], s[8:9], 0x100000
	s_lshl_b64 s[10:11], s[10:11], 19
	v_writelane_b32 v244, s10, 51
	s_ashr_i32 s19, s18, 31
	v_mul_f32_e32 v0, 0x4f7ffffe, v0
	v_writelane_b32 v244, s11, 52
	s_mov_b32 s10, s18
	v_writelane_b32 v244, s10, 53
	v_cvt_u32_f32_e32 v0, v0
	s_ashr_i32 s35, s34, 31
	v_writelane_b32 v244, s11, 54
	s_lshl_b64 s[10:11], s[18:19], 19
	v_writelane_b32 v244, s10, 55
	s_sub_i32 s22, 0, s21
	v_readfirstlane_b32 s23, v0
	v_writelane_b32 v244, s11, 56
	s_mov_b32 s10, s34
	v_writelane_b32 v244, s10, 57
	s_mul_i32 s22, s22, s23
	s_mul_hi_u32 s22, s23, s22
	v_writelane_b32 v244, s11, 58
	s_lshl_b64 s[10:11], s[34:35], 19
	v_writelane_b32 v244, s10, 59
	s_ashr_i32 s17, s16, 31
	s_add_i32 s23, s23, s22
	v_writelane_b32 v244, s11, 60
	s_mov_b32 s10, s16
	v_writelane_b32 v244, s10, 61
	s_abs_i32 s22, s9
	s_mul_hi_u32 s27, s22, s23
	v_writelane_b32 v244, s11, 62
	s_lshl_b64 s[10:11], s[16:17], 19
	v_writelane_b32 v244, s10, 63
	s_mul_i32 s27, s27, s21
	s_sub_i32 s22, s22, s27
	v_writelane_b32 v243, s11, 0
	s_mov_b32 s10, s12
	s_ashr_i32 s13, s12, 31
	v_writelane_b32 v243, s10, 1
	s_ashr_i32 s8, s9, 31
	s_sub_i32 s9, s22, s21
	v_writelane_b32 v243, s11, 2
	s_lshl_b64 s[10:11], s[12:13], 19
	s_cmp_ge_u32 s22, s21
	v_writelane_b32 v243, s10, 3
	s_cselect_b32 s9, s9, s22
	s_mov_b64 s[26:27], 0x80
	v_writelane_b32 v243, s11, 4
	s_sub_i32 s10, s9, s21
	s_cmp_ge_u32 s9, s21
	s_cselect_b32 s9, s10, s9
	s_xor_b32 s9, s9, s8
	s_sub_i32 s9, s9, s8
	s_cmp_lt_i32 s9, 32
	s_cselect_b64 s[10:11], -1, 0
	v_writelane_b32 v243, s10, 5
	s_ashr_i32 s8, s9, 31
	s_mov_b64 s[34:35], 0x100
	v_writelane_b32 v243, s11, 6
	v_writelane_b32 v243, s8, 7
	s_lshr_b32 s8, s8, 29
	s_add_i32 s8, s9, s8
	s_ashr_i32 s10, s8, 3
	s_and_b32 s8, s8, -8
	v_writelane_b32 v243, s10, 8
	s_sub_i32 s10, s9, s8
	s_cmp_gt_i32 s10, -1
	v_writelane_b32 v243, s9, 9
	s_cselect_b64 s[8:9], -1, 0
	v_writelane_b32 v243, s8, 10
	s_nop 1
	v_writelane_b32 v243, s9, 11
	s_abs_i32 s8, s7
	s_mul_hi_u32 s9, s8, s23
	s_mul_i32 s11, s9, s21
	s_sub_i32 s8, s8, s11
	s_xor_b32 s7, s7, s92
	s_lshl_b32 s11, s10, 2
	s_ashr_i32 s7, s7, 31
	v_writelane_b32 v243, s11, 12
	s_add_i32 s11, s9, 1
	s_sub_i32 s12, s8, s21
	s_cmp_ge_u32 s8, s21
	s_cselect_b32 s9, s11, s9
	s_cselect_b32 s8, s12, s8
	s_add_i32 s11, s9, 1
	s_cmp_ge_u32 s8, s21
	s_cselect_b32 s8, s11, s9
	s_xor_b32 s8, s8, s7
	s_sub_i32 s11, s8, s7
	s_cmp_gt_i32 s11, 0
	s_cselect_b64 s[8:9], -1, 0
	v_writelane_b32 v243, s8, 13
	s_add_i32 s7, s11, -1
	v_readlane_b32 s22, v246, 0
	v_writelane_b32 v243, s9, 14
	s_mul_i32 s8, s7, s31
	s_mul_hi_u32 s9, s7, s92
	s_add_i32 s9, s9, s8
	s_mul_i32 s7, s7, s92
	s_add_u32 s8, s7, s2
	s_mul_i32 s7, s10, 5
	s_addc_u32 s9, s9, s3
	v_writelane_b32 v243, s7, 15
	s_ashr_i32 s7, s8, 31
	s_lshr_b32 s7, s7, 29
	s_add_i32 s7, s8, s7
	s_and_b32 s10, s7, -8
	s_sub_i32 s10, s8, s10
	v_cmp_lt_i64_e64 s[8:9], s[8:9], v[156:157]
	s_ashr_i32 s7, s7, 3
	s_cmp_gt_i32 s10, -1
	v_writelane_b32 v243, s8, 16
	v_readlane_b32 s23, v246, 1
	s_nop 0
	v_writelane_b32 v243, s9, 17
	v_writelane_b32 v243, s7, 18
	s_cselect_b64 s[8:9], -1, 0
	v_writelane_b32 v243, s8, 19
	s_lshl_b32 s7, s10, 6
	s_lshl_b64 s[0:1], s[0:1], 1
	v_writelane_b32 v243, s9, 20
	v_writelane_b32 v243, s7, 21
	s_mul_i32 s7, s10, 0x41
	v_writelane_b32 v243, s7, 22
	v_writelane_b32 v243, s0, 23
	s_add_i32 s7, s2, s92
	s_lshl_b32 s8, s7, 2
	v_writelane_b32 v243, s1, 24
	v_writelane_b32 v243, s29, 25
	s_add_i32 s0, s6, s29
	s_and_b32 s7, s2, 3
	v_writelane_b32 v243, s0, 26
	s_lshl_b32 s7, s7, 10
	v_writelane_b32 v243, s11, 27
	s_add_i32 s0, s11, -2
	s_or_b32 s7, s29, s7
	v_writelane_b32 v243, s0, 28
	v_writelane_b32 v243, s7, 29
	s_or_b32 s6, s7, 32
	v_writelane_b32 v243, s6, 30
	v_writelane_b32 v243, s8, 31
	s_add_i32 s6, s8, 0xfffffa00
	s_lshl_b32 s0, s92, 2
	v_writelane_b32 v243, s6, 32
	v_writelane_b32 v243, s0, 33
	s_addk_i32 s0, 0xfd00
	v_writelane_b32 v243, s0, 34
	v_writelane_b32 v243, s28, 35
	s_add_i32 s0, s28, 0xffffd000
	s_lshl_b32 s1, s92, 6
	v_writelane_b32 v243, s0, 36
	v_writelane_b32 v243, s1, 37
	s_add_i32 s0, s1, 0xffffd000
	v_writelane_b32 v243, s0, 38
	s_add_i32 s0, 0, 0x20040
	v_writelane_b32 v243, s0, 39
	s_add_i32 s0, 0, 0x20044
	v_writelane_b32 v243, s0, 40
	s_lshl_b32 s0, s4, 1
	v_writelane_b32 v243, s0, 41
	s_nop 1
	v_writelane_b32 v243, s1, 42
	s_add_i32 s0, 0, 0x16e00
	v_writelane_b32 v243, s0, 43
	s_add_i32 s0, 0, 0x12c00
	v_writelane_b32 v243, s0, 44
	s_add_i32 s0, 0, 0x10200
	v_writelane_b32 v243, s0, 45
	s_lshl_b32 s0, s5, 1
	v_writelane_b32 v243, s0, 46
	s_nop 1
	v_writelane_b32 v243, s1, 47
	s_mov_b32 s0, s37
	v_writelane_b32 v243, s0, 48
	s_nop 1
	v_writelane_b32 v243, s1, 49
	v_writelane_b32 v243, s40, 50
	s_nop 1
	v_writelane_b32 v243, s41, 51
	v_writelane_b32 v243, s42, 52
	v_writelane_b32 v243, s43, 53
	v_writelane_b32 v243, s44, 54
	v_writelane_b32 v243, s45, 55
	v_writelane_b32 v243, s46, 56
	v_writelane_b32 v243, s47, 57
	v_writelane_b32 v243, s24, 58
	v_writelane_b32 v243, s48, 59
	s_nop 1
	v_writelane_b32 v243, s49, 60
	v_writelane_b32 v243, s25, 61
	v_writelane_b32 v243, s38, 62
	s_nop 1
	v_writelane_b32 v243, s39, 63
	v_writelane_b32 v247, 1, 0
	s_branch .LBB0_515

.LBB0_567:
	s_or_b64 exec, exec, s[0:1]
	v_readlane_b32 s4, v242, 2
	v_readlane_b32 s5, v242, 3
	s_mov_b64 s[0:1], -1
	s_and_b64 vcc, exec, s[4:5]
	s_waitcnt lgkmcnt(0)
	s_barrier
	v_readlane_b32 s6, v247, 0
	s_nop 3
	s_cmp_lg_u32 s6, 1
	s_cbranch_scc1 .Lseam0_cont
	v_writelane_b32 v247, 0, 0
	s_branch .LBB0_62
.Lseam0_cont:
	s_cbranch_vccz .LBB0_583
	s_mov_b64 s[6:7], s[46:47]
	v_mov_b32_e32 v83, v194
	v_readlane_b32 s4, v245, 58
	v_bfe_u32 v0, v83, 4, 2
	s_add_u32 s0, s6, 0x8200000
	v_lshlrev_b32_e32 v1, 2, v0
	v_lshl_add_u32 v82, v0, 4, 0
	v_lshlrev_b32_e32 v0, 3, v0
	v_readlane_b32 s5, v245, 59
	s_addc_u32 s1, s7, 0
	v_and_b32_e32 v84, 15, v83
	v_readfirstlane_b32 s12, v83
	s_andn2_b64 vcc, exec, s[4:5]
	v_lshlrev_b32_e32 v0, 1, v0
	v_lshlrev_b32_e32 v2, 1, v1
	s_cbranch_vccnz .LBB0_575
	v_and_b32_e32 v77, 0x7f, v83
	v_lshrrev_b32_e32 v89, 7, v83
	v_mul_u32_u24_e32 v1, 0x60, v77
	v_mul_u32_u24_e32 v85, 0x600, v77
	v_lshl_add_u32 v85, v89, 6, v85
	v_mul_u32_u24_e32 v86, 0x2200, v89
	v_lshl_add_u32 v86, v77, 1, v86
	v_and_b32_e32 v154, 15, v197
	v_lshrrev_b32_e32 v155, 4, v197
	v_mul_u32_u24_e32 v87, 0x110, v154
	v_lshl_add_u32 v87, v155, 4, v87
	v_lshlrev_b32_e32 v88, 7, v89
	v_add_u32_e32 v88, 0x9000, v88
	v_readfirstlane_b32 s19, v83
	s_nop 3
	s_lshr_b32 s19, s19, 6
	v_lshl_add_u32 v189, s19, 4, v154
	v_lshlrev_b32_e32 v90, 8, v189
	v_lshl_add_u32 v90, v155, 4, v90
	v_lshlrev_b32_e32 v91, 2, v189
	v_mul_u32_u24_e32 v92, 0x600, v189
	v_lshl_add_u32 v92, v155, 3, v92
	v_lshlrev_b32_e32 v93, 11, v189
	v_lshl_add_u32 v93, v155, 3, v93
	v_readlane_b32 s72, v246, 15
	v_readlane_b32 s73, v246, 16
	v_readlane_b32 s74, v246, 17
	v_readlane_b32 s75, v246, 18
	v_readlane_b32 s78, v246, 21
	v_readlane_b32 s79, v246, 22
	v_lshlrev_b32_e32 v77, 4, v83
	s_movk_i32 s28, 0xc0
	v_cmp_gt_u32_e32 vcc, s28, v83
	s_and_saveexec_b64 s[28:29], vcc
	s_cbranch_execz .Lgm_ng1
	global_load_dwordx4 v[200:203], v77, s[72:73]
	global_load_dwordx4 v[204:207], v77, s[74:75]

	.amdhsa_kernel _Z14fwd_megakernel4Args
		.amdhsa_group_segment_fixed_size 0
		.amdhsa_private_segment_fixed_size 0
		.amdhsa_kernarg_size 416
		.amdhsa_user_sgpr_count 2
		.amdhsa_user_sgpr_dispatch_ptr 0
		.amdhsa_user_sgpr_queue_ptr 0
		.amdhsa_user_sgpr_kernarg_segment_ptr 1
		.amdhsa_user_sgpr_dispatch_id 0
		.amdhsa_user_sgpr_kernarg_preload_length 0
		.amdhsa_user_sgpr_kernarg_preload_offset 0
		.amdhsa_user_sgpr_private_segment_size 0
		.amdhsa_uses_dynamic_stack 0
		.amdhsa_enable_private_segment 0
		.amdhsa_system_sgpr_workgroup_id_x 1
		.amdhsa_system_sgpr_workgroup_id_y 0
		.amdhsa_system_sgpr_workgroup_id_z 0
		.amdhsa_system_sgpr_workgroup_info 0
		.amdhsa_system_vgpr_workitem_id 2
		.amdhsa_next_free_vgpr 248
		.amdhsa_next_free_sgpr 102
		.amdhsa_accum_offset 248
		.amdhsa_reserve_vcc 1
		.amdhsa_float_round_mode_32 0
		.amdhsa_float_round_mode_16_64 0
		.amdhsa_float_denorm_mode_32 3
		.amdhsa_float_denorm_mode_16_64 3
		.amdhsa_dx10_clamp 1
		.amdhsa_ieee_mode 1
		.amdhsa_fp16_overflow 0
		.amdhsa_tg_split 0
		.amdhsa_exception_fp_ieee_invalid_op 0
		.amdhsa_exception_fp_denorm_src 0
		.amdhsa_exception_fp_ieee_div_zero 0
		.amdhsa_exception_fp_ieee_overflow 0
		.amdhsa_exception_fp_ieee_underflow 0
		.amdhsa_exception_fp_ieee_inexact 0
		.amdhsa_exception_int_div_zero 0
	.end_amdhsa_kernel

.Lfunc_end0:
	.size	_Z14fwd_megakernel4Args, .Lfunc_end0-_Z14fwd_megakernel4Args
	.set _Z14fwd_megakernel4Args.num_vgpr, 248
	.set _Z14fwd_megakernel4Args.num_agpr, 0
	.set _Z14fwd_megakernel4Args.numbered_sgpr, 102
	.set _Z14fwd_megakernel4Args.num_named_barrier, 0
	.set _Z14fwd_megakernel4Args.private_seg_size, 0
	.set _Z14fwd_megakernel4Args.uses_vcc, 1
	.set _Z14fwd_megakernel4Args.uses_flat_scratch, 0
	.set _Z14fwd_megakernel4Args.has_dyn_sized_stack, 0
	.set _Z14fwd_megakernel4Args.has_recursion, 0
	.set _Z14fwd_megakernel4Args.has_indirect_call, 0

amdhsa.kernels:
  - .agpr_count:     0
    .args:
      - .offset:         0
        .size:           160
        .value_kind:     by_value
      - .offset:         160
        .size:           4
        .value_kind:     hidden_block_count_x
      - .offset:         164
        .size:           4
        .value_kind:     hidden_block_count_y
      - .offset:         168
        .size:           4
        .value_kind:     hidden_block_count_z
      - .offset:         172
        .size:           2
        .value_kind:     hidden_group_size_x
      - .offset:         174
        .size:           2
        .value_kind:     hidden_group_size_y
      - .offset:         176
        .size:           2
        .value_kind:     hidden_group_size_z
      - .offset:         178
        .size:           2
        .value_kind:     hidden_remainder_x
      - .offset:         180
        .size:           2
        .value_kind:     hidden_remainder_y
      - .offset:         182
        .size:           2
        .value_kind:     hidden_remainder_z
      - .offset:         200
        .size:           8
        .value_kind:     hidden_global_offset_x
      - .offset:         208
        .size:           8
        .value_kind:     hidden_global_offset_y
      - .offset:         216
        .size:           8
        .value_kind:     hidden_global_offset_z
      - .offset:         224
        .size:           2
        .value_kind:     hidden_grid_dims
      - .offset:         248
        .size:           8
        .value_kind:     hidden_multigrid_sync_arg
      - .offset:         280
        .size:           4
        .value_kind:     hidden_dynamic_lds_size
    .group_segment_fixed_size: 0
    .kernarg_segment_align: 8
    .kernarg_segment_size: 416
    .language:       OpenCL C
    .language_version:
      - 2
      - 0
    .max_flat_workgroup_size: 512
    .name:           _Z14fwd_megakernel4Args
    .private_segment_fixed_size: 0
    .sgpr_count:     108
    .sgpr_spill_count: 272
    .symbol:         _Z14fwd_megakernel4Args.kd
    .uniform_work_group_size: 1
    .uses_dynamic_stack: false
    .vgpr_count:     248
    .vgpr_spill_count: 0
    .wavefront_size: 64
